# v33 + cg grid.sync poll interval s_sleep 1 -> 32 (less contention on the single barrier word)
# baseline (speedup 1.0000x reference)
.LBB0_54:
	s_sleep 32
	global_load_dword v2, v0, s[12:13] offset:32 sc1
	s_waitcnt vmcnt(0)
	v_and_b32_e32 v2, 0xffff0000, v2
	v_cmp_ne_u32_e32 vcc, v2, v1
	s_or_b64 s[14:15], vcc, s[14:15]
	s_andn2_b64 exec, exec, s[14:15]
	s_cbranch_execnz .LBB0_54
